# group/class barriers: L1 invalidate issued at barrier entry (overlaps the wait) when the group shares one L2
# speedup vs baseline: 1.0319x; 1.0052x over previous
; __device__ __forceinline__ unsigned xb_ld(unsigned* p)              { return __hip_atomic_load(p, __ATOMIC_RELAXED, __HIP_MEMORY_SCOPE_AGENT); }
; __device__ __forceinline__ unsigned xb_add(unsigned* p, unsigned v) { return __hip_atomic_fetch_add(p, v, __ATOMIC_RELAXED, __HIP_MEMORY_SCOPE_AGENT); }
; #define XB_SPIN(cond, bar) do { unsigned _sp = 0; while (cond) { __builtin_amdgcn_s_sleep(1); \
;     if ((++_sp & 255u) == 0u) { if (xb_ld(&(bar)[XB_TMO])) break; if (_sp > XB_SPIN_CAP) { atomicAdd(&(bar)[XB_TMO], 1u); break; } } } } while (0)
; __device__ __forceinline__ void xcd_barrier(const XcdBarrier& b) {
;     asm volatile("s_waitcnt vmcnt(0)" ::: "memory");
;     __syncthreads();
;     if (threadIdx.x == 0) {
;         unsigned* bar = b.bar;
;         __builtin_amdgcn_s_waitcnt(0);
;         unsigned nloc = b.st[0], nx = b.st[1];
;         if (nloc == 0u) { xcd_barrier_complete(bar, b.x, nloc, nx); b.st[0] = nloc; b.st[1] = nx; }
;         const unsigned old = xb_add(&bar[XB_XSUB(b.x)], 1u);
;         const unsigned gen = old / nloc;
;         if (old + 1u == (gen + 1u) * nloc) {
;             __builtin_amdgcn_fence(__ATOMIC_RELEASE, "agent");
;             asm volatile("s_waitcnt vmcnt(0)" ::: "memory");
;             const unsigned og = xb_add(&bar[XB_TOP], 1u);
;             const unsigned tg = og / nx;
;             if (og + 1u == (tg + 1u) * nx) xb_add(&bar[XB_TOPGEN], 1u);
;             else XB_SPIN(xb_ld(&bar[XB_TOPGEN]) == tg, bar);
;             __builtin_amdgcn_fence(__ATOMIC_ACQUIRE, "agent");
;             xb_add(&bar[XB_XGEN(b.x)], 1u);
;             asm volatile("s_waitcnt vmcnt(0)" ::: "memory");
;         } else {
;             XB_SPIN(xb_ld(&bar[XB_XGEN(b.x)]) == gen, bar);
;             __builtin_amdgcn_fence(__ATOMIC_ACQUIRE, "agent");
;             asm volatile("s_waitcnt vmcnt(0)" ::: "memory");
;         }
;     }
;     __syncthreads();
; }
.LBB0_322:
	s_waitcnt vmcnt(0)
	s_waitcnt vmcnt(0) lgkmcnt(0)
	s_barrier
	s_mov_b64 s[0:1], exec
	v_readlane_b32 s2, v247, 37
	v_readlane_b32 s3, v247, 38
	s_and_b64 s[2:3], s[0:1], s[2:3]
	s_mov_b64 exec, s[2:3]
	s_cbranch_execz .LBB0_374
	v_readlane_b32 s5, v247, 36
	s_and_b32 s2, s90, 7
	s_lshl_b32 s2, s2, 7
	s_add_u32 s2, s62, s2
	s_addc_u32 s3, s63, 0
	s_lshr_b32 s6, s5, 2
	s_and_b32 s6, s6, 1
	s_lshl_b32 s6, s6, 6
	s_add_u32 s6, s2, s6
	s_addc_u32 s7, s3, 0
	s_add_u32 s6, s6, 0xa800
	s_addc_u32 s7, s7, 0
	s_add_u32 s2, s2, 0xe000
	s_addc_u32 s3, s3, 0
	s_and_b32 s5, s5, 3
	s_lshl_b32 s5, s5, 3
	s_lshl_b32 s5, 32, s5
	v_mov_b32_e32 v1, 0
	global_load_dword v3, v1, s[6:7] sc1
	v_mov_b32_e32 v2, 1
	s_mov_b32 s4, 0
	s_waitcnt vmcnt(0) lgkmcnt(0)
	v_cmp_eq_u32_e32 vcc, s5, v3
	s_mov_b32 s5, 1
	s_cbranch_vccnz .Lgrpbar3_same
	s_mov_b32 s5, 0
	buffer_wbl2 sc1
	s_waitcnt vmcnt(0)
.Lgrpbar3_same:
	buffer_inv sc1
	global_atomic_add v1, v2, s[2:3]

; __device__ __forceinline__ unsigned xb_ld(unsigned* p)              { return __hip_atomic_load(p, __ATOMIC_RELAXED, __HIP_MEMORY_SCOPE_AGENT); }
; __device__ __forceinline__ unsigned xb_add(unsigned* p, unsigned v) { return __hip_atomic_fetch_add(p, v, __ATOMIC_RELAXED, __HIP_MEMORY_SCOPE_AGENT); }
; #define XB_SPIN(cond, bar) do { unsigned _sp = 0; while (cond) { __builtin_amdgcn_s_sleep(1); \
;     if ((++_sp & 255u) == 0u) { if (xb_ld(&(bar)[XB_TMO])) break; if (_sp > XB_SPIN_CAP) { atomicAdd(&(bar)[XB_TMO], 1u); break; } } } } while (0)
; __device__ __forceinline__ void xcd_barrier(const XcdBarrier& b) {
;     ...
;             else XB_SPIN(xb_ld(&bar[XB_TOPGEN]) == tg, bar);
;             __builtin_amdgcn_fence(__ATOMIC_ACQUIRE, "agent");
;             xb_add(&bar[XB_XGEN(b.x)], 1u);
;             asm volatile("s_waitcnt vmcnt(0)" ::: "memory");
;         } else {
;             XB_SPIN(xb_ld(&bar[XB_XGEN(b.x)]) == gen, bar);
;             __builtin_amdgcn_fence(__ATOMIC_ACQUIRE, "agent");
;             asm volatile("s_waitcnt vmcnt(0)" ::: "memory");
;         }
;     }
;     __syncthreads();
; }
.Lgrpbar3_done:
	s_cmp_eq_u32 s5, 1
	s_cbranch_scc1 .Lgrpbar3_noinv
	buffer_inv sc1
	s_waitcnt vmcnt(0)
.Lgrpbar3_noinv:
.LBB0_374:
	s_or_b64 exec, exec, s[0:1]
	s_waitcnt lgkmcnt(0)
	s_barrier

; __device__ __forceinline__ unsigned xb_ld(unsigned* p)              { return __hip_atomic_load(p, __ATOMIC_RELAXED, __HIP_MEMORY_SCOPE_AGENT); }
; __device__ __forceinline__ unsigned xb_add(unsigned* p, unsigned v) { return __hip_atomic_fetch_add(p, v, __ATOMIC_RELAXED, __HIP_MEMORY_SCOPE_AGENT); }
; #define XB_SPIN(cond, bar) do { unsigned _sp = 0; while (cond) { __builtin_amdgcn_s_sleep(1); \
;     if ((++_sp & 255u) == 0u) { if (xb_ld(&(bar)[XB_TMO])) break; if (_sp > XB_SPIN_CAP) { atomicAdd(&(bar)[XB_TMO], 1u); break; } } } } while (0)
; __device__ __forceinline__ void xcd_barrier(const XcdBarrier& b) {
;     asm volatile("s_waitcnt vmcnt(0)" ::: "memory");
;     __syncthreads();
;     if (threadIdx.x == 0) {
;         unsigned* bar = b.bar;
;         __builtin_amdgcn_s_waitcnt(0);
;         unsigned nloc = b.st[0], nx = b.st[1];
;         if (nloc == 0u) { xcd_barrier_complete(bar, b.x, nloc, nx); b.st[0] = nloc; b.st[1] = nx; }
;         const unsigned old = xb_add(&bar[XB_XSUB(b.x)], 1u);
;         const unsigned gen = old / nloc;
;         if (old + 1u == (gen + 1u) * nloc) {
;             __builtin_amdgcn_fence(__ATOMIC_RELEASE, "agent");
;             asm volatile("s_waitcnt vmcnt(0)" ::: "memory");
;             const unsigned og = xb_add(&bar[XB_TOP], 1u);
;             const unsigned tg = og / nx;
;             if (og + 1u == (tg + 1u) * nx) xb_add(&bar[XB_TOPGEN], 1u);
;             else XB_SPIN(xb_ld(&bar[XB_TOPGEN]) == tg, bar);
;             __builtin_amdgcn_fence(__ATOMIC_ACQUIRE, "agent");
;             xb_add(&bar[XB_XGEN(b.x)], 1u);
;             asm volatile("s_waitcnt vmcnt(0)" ::: "memory");
;         } else {
;             XB_SPIN(xb_ld(&bar[XB_XGEN(b.x)]) == gen, bar);
;             __builtin_amdgcn_fence(__ATOMIC_ACQUIRE, "agent");
;             asm volatile("s_waitcnt vmcnt(0)" ::: "memory");
;         }
;     }
;     __syncthreads();
; }
.LBB0_729:
	s_waitcnt vmcnt(0)
	s_waitcnt vmcnt(0) lgkmcnt(0)
	s_barrier
	s_mov_b64 s[0:1], exec
	v_readlane_b32 s2, v247, 37
	v_readlane_b32 s3, v247, 38
	s_and_b64 s[2:3], s[0:1], s[2:3]
	s_mov_b64 exec, s[2:3]
	s_cbranch_execz .LBB0_781
	v_readlane_b32 s5, v247, 36
	s_and_b32 s2, s90, 31
	s_lshl_b32 s2, s2, 6
	s_add_u32 s2, s62, s2
	s_addc_u32 s3, s63, 0
	s_add_u32 s6, s2, 0xa000
	s_addc_u32 s7, s3, 0
	s_add_u32 s2, s2, 0xb000
	s_addc_u32 s3, s3, 0
	s_and_b32 s5, s5, 7
	s_lshl_b32 s5, s5, 2
	s_lshl_b32 s5, 8, s5
	v_mov_b32_e32 v1, 0
	global_load_dword v3, v1, s[6:7] sc1
	v_mov_b32_e32 v2, 1
	s_mov_b32 s4, 0
	s_add_u32 s6, s62, 0xc000
	s_addc_u32 s7, s63, 0
	s_waitcnt vmcnt(0) lgkmcnt(0)
	v_cmp_eq_u32_e32 vcc, s5, v3
	s_mov_b32 s5, 1
	s_cbranch_vccnz .Lgrpbar2_same
	s_mov_b32 s5, 0
	buffer_wbl2 sc1
	s_waitcnt vmcnt(0)
.Lgrpbar2_same:
	buffer_inv sc1
	global_atomic_add v1, v2, s[2:3]
	global_atomic_add v1, v2, s[6:7]

; __device__ __forceinline__ unsigned xb_ld(unsigned* p)              { return __hip_atomic_load(p, __ATOMIC_RELAXED, __HIP_MEMORY_SCOPE_AGENT); }
; __device__ __forceinline__ unsigned xb_add(unsigned* p, unsigned v) { return __hip_atomic_fetch_add(p, v, __ATOMIC_RELAXED, __HIP_MEMORY_SCOPE_AGENT); }
; #define XB_SPIN(cond, bar) do { unsigned _sp = 0; while (cond) { __builtin_amdgcn_s_sleep(1); \
;     if ((++_sp & 255u) == 0u) { if (xb_ld(&(bar)[XB_TMO])) break; if (_sp > XB_SPIN_CAP) { atomicAdd(&(bar)[XB_TMO], 1u); break; } } } } while (0)
; __device__ __forceinline__ void xcd_barrier(const XcdBarrier& b) {
;     asm volatile("s_waitcnt vmcnt(0)" ::: "memory");
;     __syncthreads();
;     if (threadIdx.x == 0) {
;         unsigned* bar = b.bar;
;         __builtin_amdgcn_s_waitcnt(0);
;         unsigned nloc = b.st[0], nx = b.st[1];
;         if (nloc == 0u) { xcd_barrier_complete(bar, b.x, nloc, nx); b.st[0] = nloc; b.st[1] = nx; }
;         const unsigned old = xb_add(&bar[XB_XSUB(b.x)], 1u);
;         const unsigned gen = old / nloc;
;         if (old + 1u == (gen + 1u) * nloc) {
;             __builtin_amdgcn_fence(__ATOMIC_RELEASE, "agent");
;             asm volatile("s_waitcnt vmcnt(0)" ::: "memory");
;             const unsigned og = xb_add(&bar[XB_TOP], 1u);
;             const unsigned tg = og / nx;
;             if (og + 1u == (tg + 1u) * nx) xb_add(&bar[XB_TOPGEN], 1u);
;             else XB_SPIN(xb_ld(&bar[XB_TOPGEN]) == tg, bar);
;             __builtin_amdgcn_fence(__ATOMIC_ACQUIRE, "agent");
;             xb_add(&bar[XB_XGEN(b.x)], 1u);
;             asm volatile("s_waitcnt vmcnt(0)" ::: "memory");
;         } else {
;             XB_SPIN(xb_ld(&bar[XB_XGEN(b.x)]) == gen, bar);
;             __builtin_amdgcn_fence(__ATOMIC_ACQUIRE, "agent");
;             asm volatile("s_waitcnt vmcnt(0)" ::: "memory");
;         }
;     }
;     __syncthreads();
; }
.LBB0_823:
	s_cmp_lt_i32 s19, 7
	s_cbranch_scc1 .LBB0_877
	s_waitcnt vmcnt(0)
	s_waitcnt vmcnt(0) lgkmcnt(0)
	s_barrier
	s_mov_b64 s[0:1], exec
	v_readlane_b32 s2, v247, 37
	v_readlane_b32 s3, v247, 38
	s_and_b64 s[2:3], s[0:1], s[2:3]
	s_mov_b64 exec, s[2:3]
	s_cbranch_execz .LBB0_876
	v_readlane_b32 s5, v247, 36
	s_and_b32 s2, s90, 31
	s_lshl_b32 s2, s2, 6
	s_add_u32 s2, s62, s2
	s_addc_u32 s3, s63, 0
	s_add_u32 s6, s2, 0xa000
	s_addc_u32 s7, s3, 0
	s_add_u32 s2, s2, 0x8000
	s_addc_u32 s3, s3, 0
	s_and_b32 s5, s5, 7
	s_lshl_b32 s5, s5, 2
	s_lshl_b32 s5, 8, s5
	v_mov_b32_e32 v1, 0
	global_load_dword v3, v1, s[6:7] sc1
	v_mov_b32_e32 v2, 1
	s_mov_b32 s4, 0
	s_add_u32 s6, s62, 0xc000
	s_addc_u32 s7, s63, 0
	s_waitcnt vmcnt(0) lgkmcnt(0)
	v_cmp_eq_u32_e32 vcc, s5, v3
	s_mov_b32 s5, 1
	s_cbranch_vccnz .Lgrpbar1_same
	s_mov_b32 s5, 0
	buffer_wbl2 sc1
	s_waitcnt vmcnt(0)

; __device__ __forceinline__ unsigned xb_ld(unsigned* p)              { return __hip_atomic_load(p, __ATOMIC_RELAXED, __HIP_MEMORY_SCOPE_AGENT); }
; __device__ __forceinline__ unsigned xb_add(unsigned* p, unsigned v) { return __hip_atomic_fetch_add(p, v, __ATOMIC_RELAXED, __HIP_MEMORY_SCOPE_AGENT); }
; #define XB_SPIN(cond, bar) do { unsigned _sp = 0; while (cond) { __builtin_amdgcn_s_sleep(1); \
;     if ((++_sp & 255u) == 0u) { if (xb_ld(&(bar)[XB_TMO])) break; if (_sp > XB_SPIN_CAP) { atomicAdd(&(bar)[XB_TMO], 1u); break; } } } } while (0)
; __device__ __forceinline__ void xcd_barrier(const XcdBarrier& b) {
;     asm volatile("s_waitcnt vmcnt(0)" ::: "memory");
;     __syncthreads();
;     if (threadIdx.x == 0) {
;         unsigned* bar = b.bar;
;         __builtin_amdgcn_s_waitcnt(0);
;         unsigned nloc = b.st[0], nx = b.st[1];
;         if (nloc == 0u) { xcd_barrier_complete(bar, b.x, nloc, nx); b.st[0] = nloc; b.st[1] = nx; }
;         const unsigned old = xb_add(&bar[XB_XSUB(b.x)], 1u);
;         const unsigned gen = old / nloc;
;         if (old + 1u == (gen + 1u) * nloc) {
;             __builtin_amdgcn_fence(__ATOMIC_RELEASE, "agent");
;             asm volatile("s_waitcnt vmcnt(0)" ::: "memory");
;             const unsigned og = xb_add(&bar[XB_TOP], 1u);
;             const unsigned tg = og / nx;
;             if (og + 1u == (tg + 1u) * nx) xb_add(&bar[XB_TOPGEN], 1u);
;             else XB_SPIN(xb_ld(&bar[XB_TOPGEN]) == tg, bar);
;             __builtin_amdgcn_fence(__ATOMIC_ACQUIRE, "agent");
;             xb_add(&bar[XB_XGEN(b.x)], 1u);
;             asm volatile("s_waitcnt vmcnt(0)" ::: "memory");
;         } else {
;             XB_SPIN(xb_ld(&bar[XB_XGEN(b.x)]) == gen, bar);
;             __builtin_amdgcn_fence(__ATOMIC_ACQUIRE, "agent");
;             asm volatile("s_waitcnt vmcnt(0)" ::: "memory");
;         }
;     }
;     __syncthreads();
; }
.LBB0_902:
	s_cmp_lt_i32 s19, 9
	s_cbranch_scc1 .LBB0_956
	s_waitcnt vmcnt(0)
	s_waitcnt vmcnt(0) lgkmcnt(0)
	s_barrier
	s_mov_b64 s[0:1], exec
	v_readlane_b32 s2, v247, 37
	v_readlane_b32 s3, v247, 38
	s_and_b64 s[2:3], s[0:1], s[2:3]
	s_mov_b64 exec, s[2:3]
	s_cbranch_execz .LBB0_955
	v_readlane_b32 s5, v247, 36
	s_and_b32 s2, s90, 31
	s_lshl_b32 s2, s2, 6
	s_add_u32 s2, s62, s2
	s_addc_u32 s3, s63, 0
	s_add_u32 s6, s2, 0xa000
	s_addc_u32 s7, s3, 0
	s_add_u32 s2, s2, 0x9000
	s_addc_u32 s3, s3, 0
	s_and_b32 s5, s5, 7
	s_lshl_b32 s5, s5, 2
	s_lshl_b32 s5, 8, s5
	v_mov_b32_e32 v1, 0
	global_load_dword v3, v1, s[6:7] sc1
	v_mov_b32_e32 v2, 1
	s_mov_b32 s4, 0
	s_add_u32 s6, s62, 0xc000
	s_addc_u32 s7, s63, 0
	s_waitcnt vmcnt(0) lgkmcnt(0)
	v_cmp_eq_u32_e32 vcc, s5, v3
	s_mov_b32 s5, 1
	s_cbranch_vccnz .Lgrpbar0_same
	s_mov_b32 s5, 0
	buffer_wbl2 sc1
	s_waitcnt vmcnt(0)
